# v77 + prep_run pooling window-sum loops (5 copies): the four row loads of the unrolled body issued together with counted waits instead of load/wait(0) four times
# baseline (speedup 1.0000x reference)
.LBB0_440:
	v_lshl_add_u64 v[66:67], v[48:49], 0, v[54:55]
	v_lshl_add_u64 v[224:225], v[48:49], 0, v[52:53]
	v_lshl_add_u64 v[226:227], v[48:49], 0, v[50:51]
	v_lshl_add_u64 v[228:229], v[48:49], 0, v[46:47]
	global_load_dwordx2 v[66:67], v[66:67], off
	global_load_dwordx2 v[224:225], v[224:225], off
	global_load_dwordx2 v[226:227], v[226:227], off
	global_load_dwordx2 v[228:229], v[228:229], off
	v_add_u32_e32 v19, 4, v19
	v_cmp_ge_u32_e64 s[0:1], v19, v17
	s_or_b64 s[10:11], s[0:1], s[10:11]
	v_lshl_add_u64 v[48:49], v[48:49], 0, s[30:31]
	s_waitcnt vmcnt(3)
	v_lshlrev_b32_e32 v68, 16, v66
	v_and_b32_e32 v69, 0xffff0000, v66
	v_lshlrev_b32_e32 v66, 16, v67
	v_and_b32_e32 v67, 0xffff0000, v67
	v_pk_add_f32 v[38:39], v[38:39], v[66:67]
	v_pk_add_f32 v[40:41], v[40:41], v[68:69]
	s_waitcnt vmcnt(2)
	v_lshlrev_b32_e32 v68, 16, v224
	v_and_b32_e32 v69, 0xffff0000, v224
	v_lshlrev_b32_e32 v66, 16, v225
	v_and_b32_e32 v67, 0xffff0000, v225
	v_pk_add_f32 v[38:39], v[38:39], v[66:67]
	v_pk_add_f32 v[40:41], v[40:41], v[68:69]
	s_waitcnt vmcnt(1)
	v_lshlrev_b32_e32 v68, 16, v226
	v_and_b32_e32 v69, 0xffff0000, v226
	v_lshlrev_b32_e32 v66, 16, v227
	v_and_b32_e32 v67, 0xffff0000, v227
	v_pk_add_f32 v[38:39], v[38:39], v[66:67]
	v_pk_add_f32 v[40:41], v[40:41], v[68:69]
	s_waitcnt vmcnt(0)
	v_lshlrev_b32_e32 v68, 16, v228
	v_and_b32_e32 v69, 0xffff0000, v228
	v_lshlrev_b32_e32 v66, 16, v229
	v_and_b32_e32 v67, 0xffff0000, v229
	v_pk_add_f32 v[38:39], v[38:39], v[66:67]
	v_pk_add_f32 v[40:41], v[40:41], v[68:69]
	s_andn2_b64 exec, exec, s[10:11]
	s_cbranch_execnz .LBB0_440
	s_or_b64 exec, exec, s[10:11]

.LBB0_469:
	v_lshl_add_u64 v[66:67], v[50:51], 0, v[56:57]
	v_lshl_add_u64 v[224:225], v[50:51], 0, v[54:55]
	v_lshl_add_u64 v[226:227], v[50:51], 0, v[52:53]
	v_lshl_add_u64 v[228:229], v[50:51], 0, v[48:49]
	global_load_dwordx2 v[66:67], v[66:67], off
	global_load_dwordx2 v[224:225], v[224:225], off
	global_load_dwordx2 v[226:227], v[226:227], off
	global_load_dwordx2 v[228:229], v[228:229], off
	v_add_u32_e32 v17, 4, v17
	v_cmp_ge_u32_e64 s[0:1], v17, v19
	s_or_b64 s[10:11], s[0:1], s[10:11]
	v_lshl_add_u64 v[50:51], v[50:51], 0, s[30:31]
	s_waitcnt vmcnt(3)
	v_lshlrev_b32_e32 v68, 16, v66
	v_and_b32_e32 v69, 0xffff0000, v66
	v_lshlrev_b32_e32 v66, 16, v67
	v_and_b32_e32 v67, 0xffff0000, v67
	v_pk_add_f32 v[40:41], v[40:41], v[66:67]
	v_pk_add_f32 v[42:43], v[42:43], v[68:69]
	s_waitcnt vmcnt(2)
	v_lshlrev_b32_e32 v68, 16, v224
	v_and_b32_e32 v69, 0xffff0000, v224
	v_lshlrev_b32_e32 v66, 16, v225
	v_and_b32_e32 v67, 0xffff0000, v225
	v_pk_add_f32 v[40:41], v[40:41], v[66:67]
	v_pk_add_f32 v[42:43], v[42:43], v[68:69]
	s_waitcnt vmcnt(1)
	v_lshlrev_b32_e32 v68, 16, v226
	v_and_b32_e32 v69, 0xffff0000, v226
	v_lshlrev_b32_e32 v66, 16, v227
	v_and_b32_e32 v67, 0xffff0000, v227
	v_pk_add_f32 v[40:41], v[40:41], v[66:67]
	v_pk_add_f32 v[42:43], v[42:43], v[68:69]
	s_waitcnt vmcnt(0)
	v_lshlrev_b32_e32 v68, 16, v228
	v_and_b32_e32 v69, 0xffff0000, v228
	v_lshlrev_b32_e32 v66, 16, v229
	v_and_b32_e32 v67, 0xffff0000, v229
	v_pk_add_f32 v[40:41], v[40:41], v[66:67]
	v_pk_add_f32 v[42:43], v[42:43], v[68:69]
	s_andn2_b64 exec, exec, s[10:11]
	s_cbranch_execnz .LBB0_469
	s_or_b64 exec, exec, s[10:11]

.LBB0_494:
	v_lshl_add_u64 v[66:67], v[50:51], 0, v[56:57]
	v_lshl_add_u64 v[224:225], v[50:51], 0, v[54:55]
	v_lshl_add_u64 v[226:227], v[50:51], 0, v[52:53]
	v_lshl_add_u64 v[228:229], v[50:51], 0, v[48:49]
	global_load_dwordx2 v[66:67], v[66:67], off
	global_load_dwordx2 v[224:225], v[224:225], off
	global_load_dwordx2 v[226:227], v[226:227], off
	global_load_dwordx2 v[228:229], v[228:229], off
	v_add_u32_e32 v17, 4, v17
	v_cmp_ge_u32_e64 s[0:1], v17, v19
	s_or_b64 s[8:9], s[0:1], s[8:9]
	v_lshl_add_u64 v[50:51], v[50:51], 0, s[30:31]
	s_waitcnt vmcnt(3)
	v_lshlrev_b32_e32 v68, 16, v66
	v_and_b32_e32 v69, 0xffff0000, v66
	v_lshlrev_b32_e32 v66, 16, v67
	v_and_b32_e32 v67, 0xffff0000, v67
	v_pk_add_f32 v[40:41], v[40:41], v[66:67]
	v_pk_add_f32 v[42:43], v[42:43], v[68:69]
	s_waitcnt vmcnt(2)
	v_lshlrev_b32_e32 v68, 16, v224
	v_and_b32_e32 v69, 0xffff0000, v224
	v_lshlrev_b32_e32 v66, 16, v225
	v_and_b32_e32 v67, 0xffff0000, v225
	v_pk_add_f32 v[40:41], v[40:41], v[66:67]
	v_pk_add_f32 v[42:43], v[42:43], v[68:69]
	s_waitcnt vmcnt(1)
	v_lshlrev_b32_e32 v68, 16, v226
	v_and_b32_e32 v69, 0xffff0000, v226
	v_lshlrev_b32_e32 v66, 16, v227
	v_and_b32_e32 v67, 0xffff0000, v227
	v_pk_add_f32 v[40:41], v[40:41], v[66:67]
	v_pk_add_f32 v[42:43], v[42:43], v[68:69]
	s_waitcnt vmcnt(0)
	v_lshlrev_b32_e32 v68, 16, v228
	v_and_b32_e32 v69, 0xffff0000, v228
	v_lshlrev_b32_e32 v66, 16, v229
	v_and_b32_e32 v67, 0xffff0000, v229
	v_pk_add_f32 v[40:41], v[40:41], v[66:67]
	v_pk_add_f32 v[42:43], v[42:43], v[68:69]
	s_andn2_b64 exec, exec, s[8:9]
	s_cbranch_execnz .LBB0_494
	s_or_b64 exec, exec, s[8:9]

.LBB0_524:
	v_lshl_add_u64 v[62:63], v[46:47], 0, v[52:53]
	v_lshl_add_u64 v[224:225], v[46:47], 0, v[50:51]
	v_lshl_add_u64 v[226:227], v[46:47], 0, v[48:49]
	v_lshl_add_u64 v[228:229], v[46:47], 0, v[44:45]
	global_load_dwordx2 v[62:63], v[62:63], off
	global_load_dwordx2 v[224:225], v[224:225], off
	global_load_dwordx2 v[226:227], v[226:227], off
	global_load_dwordx2 v[228:229], v[228:229], off
	v_add_u32_e32 v19, 4, v19
	v_cmp_ge_u32_e64 s[0:1], v19, v17
	s_or_b64 s[10:11], s[0:1], s[10:11]
	v_lshl_add_u64 v[46:47], v[46:47], 0, s[30:31]
	s_waitcnt vmcnt(3)
	v_lshlrev_b32_e32 v64, 16, v62
	v_and_b32_e32 v65, 0xffff0000, v62
	v_lshlrev_b32_e32 v62, 16, v63
	v_and_b32_e32 v63, 0xffff0000, v63
	v_pk_add_f32 v[38:39], v[38:39], v[62:63]
	v_pk_add_f32 v[36:37], v[36:37], v[64:65]
	s_waitcnt vmcnt(2)
	v_lshlrev_b32_e32 v64, 16, v224
	v_and_b32_e32 v65, 0xffff0000, v224
	v_lshlrev_b32_e32 v62, 16, v225
	v_and_b32_e32 v63, 0xffff0000, v225
	v_pk_add_f32 v[38:39], v[38:39], v[62:63]
	v_pk_add_f32 v[36:37], v[36:37], v[64:65]
	s_waitcnt vmcnt(1)
	v_lshlrev_b32_e32 v64, 16, v226
	v_and_b32_e32 v65, 0xffff0000, v226
	v_lshlrev_b32_e32 v62, 16, v227
	v_and_b32_e32 v63, 0xffff0000, v227
	v_pk_add_f32 v[38:39], v[38:39], v[62:63]
	v_pk_add_f32 v[36:37], v[36:37], v[64:65]
	s_waitcnt vmcnt(0)
	v_lshlrev_b32_e32 v64, 16, v228
	v_and_b32_e32 v65, 0xffff0000, v228
	v_lshlrev_b32_e32 v62, 16, v229
	v_and_b32_e32 v63, 0xffff0000, v229
	v_pk_add_f32 v[38:39], v[38:39], v[62:63]
	v_pk_add_f32 v[36:37], v[36:37], v[64:65]
	s_andn2_b64 exec, exec, s[10:11]
	s_cbranch_execnz .LBB0_524
	s_or_b64 exec, exec, s[10:11]

.LBB0_550:
	v_lshl_add_u64 v[64:65], v[48:49], 0, v[54:55]
	v_lshl_add_u64 v[224:225], v[48:49], 0, v[52:53]
	v_lshl_add_u64 v[226:227], v[48:49], 0, v[50:51]
	v_lshl_add_u64 v[228:229], v[48:49], 0, v[46:47]
	global_load_dwordx2 v[64:65], v[64:65], off
	global_load_dwordx2 v[224:225], v[224:225], off
	global_load_dwordx2 v[226:227], v[226:227], off
	global_load_dwordx2 v[228:229], v[228:229], off
	v_add_u32_e32 v19, 4, v19
	v_cmp_ge_u32_e64 s[0:1], v19, v17
	s_or_b64 s[10:11], s[0:1], s[10:11]
	v_lshl_add_u64 v[48:49], v[48:49], 0, s[30:31]
	s_waitcnt vmcnt(3)
	v_lshlrev_b32_e32 v66, 16, v64
	v_and_b32_e32 v67, 0xffff0000, v64
	v_lshlrev_b32_e32 v64, 16, v65
	v_and_b32_e32 v65, 0xffff0000, v65
	v_pk_add_f32 v[38:39], v[38:39], v[64:65]
	v_pk_add_f32 v[40:41], v[40:41], v[66:67]
	s_waitcnt vmcnt(2)
	v_lshlrev_b32_e32 v66, 16, v224
	v_and_b32_e32 v67, 0xffff0000, v224
	v_lshlrev_b32_e32 v64, 16, v225
	v_and_b32_e32 v65, 0xffff0000, v225
	v_pk_add_f32 v[38:39], v[38:39], v[64:65]
	v_pk_add_f32 v[40:41], v[40:41], v[66:67]
	s_waitcnt vmcnt(1)
	v_lshlrev_b32_e32 v66, 16, v226
	v_and_b32_e32 v67, 0xffff0000, v226
	v_lshlrev_b32_e32 v64, 16, v227
	v_and_b32_e32 v65, 0xffff0000, v227
	v_pk_add_f32 v[38:39], v[38:39], v[64:65]
	v_pk_add_f32 v[40:41], v[40:41], v[66:67]
	s_waitcnt vmcnt(0)
	v_lshlrev_b32_e32 v66, 16, v228
	v_and_b32_e32 v67, 0xffff0000, v228
	v_lshlrev_b32_e32 v64, 16, v229
	v_and_b32_e32 v65, 0xffff0000, v229
	v_pk_add_f32 v[38:39], v[38:39], v[64:65]
	v_pk_add_f32 v[40:41], v[40:41], v[66:67]
	s_andn2_b64 exec, exec, s[10:11]
	s_cbranch_execnz .LBB0_550
	s_or_b64 exec, exec, s[10:11]
